# adds: attention fast loop drops dead SCC save/restore at the two DMA sites and the duplicate vmcnt(0) before the loop barrier
# baseline (speedup 1.0000x reference)
; __device__ __forceinline__ void attn_unit(const bf16* Hb, const bf16* KD, const bf16* VD, bf16* MIX, int row0, int S, int head, int qb, float lam, const float* dng, float kn0, float kn1, LAS unsigned char* lds, int wave_u) {
;     ...
;         if (t + 2 <= thi) { ATT_DMA(t + 2, 2 * (pbuf ^ 1)); ATT_DMA(t + 3, 2 * (pbuf ^ 1) + 1); }
.LBB0_656:
	v_pk_add_f32 v[156:157], v[156:157], v[158:159]
	v_pk_add_f32 v[158:159], v[162:163], v[166:167]
	v_pk_add_f32 v[126:127], v[126:127], v[128:129]
	v_pk_add_f32 v[156:157], v[156:157], v[158:159]
	v_pk_add_f32 v[158:159], v[160:161], v[164:165]
	v_pk_add_f32 v[160:161], v[168:169], v[170:171]
	v_pk_add_f32 v[154:155], v[154:155], v[156:157]
	v_pk_add_f32 v[158:159], v[158:159], v[160:161]
	v_pk_add_f32 v[128:129], v[132:133], v[152:153]
	v_pk_add_f32 v[154:155], v[158:159], v[154:155]
	v_pk_add_f32 v[126:127], v[126:127], v[128:129]
	v_pk_add_f32 v[128:129], v[130:131], v[150:151]
	v_pk_add_f32 v[130:131], v[194:195], v[196:197]
	v_pk_add_f32 v[126:127], v[154:155], v[126:127]
	v_pk_add_f32 v[128:129], v[128:129], v[130:131]
	s_waitcnt lgkmcnt(0)
	s_nop 0
	v_pk_add_f32 v[194:195], v[128:129], v[126:127]
	ds_read_b64_tr_b16 v[126:127], v230 offset:8192
	ds_read_b64_tr_b16 v[128:129], v229 offset:8192
	ds_read_b64_tr_b16 v[130:131], v228 offset:8192
	ds_read_b64_tr_b16 v[132:133], v227 offset:8192
	ds_read_b64_tr_b16 v[150:151], v234 offset:8192
	ds_read_b64_tr_b16 v[152:153], v233 offset:8192
	ds_read_b64_tr_b16 v[154:155], v232 offset:8192
	ds_read_b64_tr_b16 v[156:157], v231 offset:8192
	ds_read_b128 v[170:173], v173 offset:40960
	ds_read_b128 v[166:169], v235 offset:40960
	ds_read_b128 v[162:165], v236 offset:40960
	ds_read_b128 v[158:161], v237 offset:40960
	s_waitcnt lgkmcnt(0)
	v_mfma_f32_32x32x16_bf16 v[82:97], v[170:173], v[98:101], v[82:97]
	v_exp_f32_e32 v66, v66
	v_exp_f32_e32 v67, v67
	v_exp_f32_e32 v68, v68
	v_exp_f32_e32 v69, v69
	v_exp_f32_e32 v70, v70
	v_exp_f32_e32 v71, v71
	v_exp_f32_e32 v72, v72
	v_mfma_f32_32x32x16_bf16 v[82:97], v[166:169], v[102:105], v[82:97]
	v_exp_f32_e32 v73, v73
	v_mfma_f32_32x32x16_bf16 v[50:65], v[134:137], v[118:121], v[50:65]
	v_mfma_f32_32x32x16_bf16 v[34:49], v[138:141], v[118:121], v[34:49]
	v_mfma_f32_32x32x16_bf16 v[18:33], v[142:145], v[118:121], v[18:33]
	v_mfma_f32_32x32x16_bf16 v[2:17], v[146:149], v[118:121], v[2:17]
	v_add_f32_e64 v118, v66, v68
	v_add_f32_e64 v119, v67, v69
	v_add_f32_e64 v120, v70, v72
	v_add_f32_e64 v121, v71, v73
	v_cvt_pk_bf16_f32 v66, v66, v67
	v_cvt_pk_bf16_f32 v67, v68, v69
	v_cvt_pk_bf16_f32 v68, v70, v71
	v_cvt_pk_bf16_f32 v69, v72, v73
	v_exp_f32_e32 v70, v74
	v_mfma_f32_32x32x16_bf16 v[82:97], v[162:165], v[106:109], v[82:97]
	v_exp_f32_e32 v71, v75
	v_exp_f32_e32 v72, v76
	v_exp_f32_e32 v73, v77
	v_exp_f32_e32 v74, v78
	v_exp_f32_e32 v75, v79
	v_exp_f32_e32 v76, v80
	v_exp_f32_e32 v77, v81
	v_pk_add_f32 v[118:119], v[118:119], v[120:121]
	v_pk_add_f32 v[78:79], v[70:71], v[72:73]
	v_cvt_pk_bf16_f32 v70, v70, v71
	v_pk_add_f32 v[80:81], v[74:75], v[76:77]
	v_cvt_pk_bf16_f32 v71, v72, v73
	v_cvt_pk_bf16_f32 v72, v74, v75
	v_cvt_pk_bf16_f32 v73, v76, v77
	v_mfma_f32_32x32x16_bf16 v[82:97], v[158:161], v[110:113], v[82:97]
	v_add_f32_e64 v120, v78, v80
	v_add_f32_e64 v121, v79, v81
	s_waitcnt lgkmcnt(0)
	ds_read_b64_tr_b16 v[78:79], v230 offset:12288
	ds_read_b64_tr_b16 v[80:81], v229 offset:12288
	ds_read_b64_tr_b16 v[134:135], v228 offset:12288
	ds_read_b64_tr_b16 v[136:137], v227 offset:12288
	ds_read_b64_tr_b16 v[138:139], v234 offset:12288
	ds_read_b64_tr_b16 v[140:141], v233 offset:12288
	ds_read_b64_tr_b16 v[142:143], v232 offset:12288
	ds_read_b64_tr_b16 v[144:145], v231 offset:12288
	v_add_f32_e64 v74, v194, v118
	v_add_f32_e64 v75, v195, v119
	v_add_f32_e64 v146, v120, v74
	v_add_f32_e64 v147, v121, v75
	s_nop 5
	v_exp_f32_e32 v74, v82
	v_exp_f32_e32 v75, v83
	v_exp_f32_e32 v76, v84
	v_exp_f32_e32 v77, v85
	v_exp_f32_e32 v82, v86
	v_exp_f32_e32 v83, v87
	v_exp_f32_e32 v84, v88
	v_exp_f32_e32 v85, v89
	v_mfma_f32_32x32x16_bf16 v[50:65], v[126:129], v[122:125], v[50:65]
	v_add_f32_e64 v86, v74, v76
	v_add_f32_e64 v87, v75, v77
	v_cvt_pk_bf16_f32 v74, v74, v75
	v_add_f32_e64 v88, v82, v84
	v_add_f32_e64 v89, v83, v85
	v_cvt_pk_bf16_f32 v75, v76, v77
	v_cvt_pk_bf16_f32 v76, v82, v83
	v_cvt_pk_bf16_f32 v77, v84, v85
	v_add_f32_e64 v126, v86, v88
	v_add_f32_e64 v127, v87, v89
	v_mfma_f32_32x32x16_bf16 v[34:49], v[130:133], v[122:125], v[34:49]
	v_mfma_f32_32x32x16_bf16 v[18:33], v[150:153], v[122:125], v[18:33]
	v_mfma_f32_32x32x16_bf16 v[2:17], v[154:157], v[122:125], v[2:17]
	s_cmp_le_i32 s73, s74
	s_cbranch_scc0 .Ldma_skip_1
	v_add_u32_e32 v250, 0x4000, v250
	v_add_u32_e32 v254, 0x4000, v254
	s_add_i32 m0, s84, 0x8000
	s_nop 0
	global_load_lds_dwordx4 v250, s[80:81]
	s_add_i32 m0, s84, 0x8400
	s_nop 0
	global_load_lds_dwordx4 v254, s[80:81]
	s_add_i32 m0, s84, 0xc000
	s_nop 0
	global_load_lds_dwordx4 v250, s[82:83]
	s_add_i32 m0, s84, 0xc400
	s_nop 0
	global_load_lds_dwordx4 v254, s[82:83]
; __device__ __forceinline__ void attn_unit(const bf16* Hb, const bf16* KD, const bf16* VD, bf16* MIX, int row0, int S, int head, int qb, float lam, const float* dng, float kn0, float kn1, LAS unsigned char* lds, int wave_u) {
;     ...
;         asm volatile("s_waitcnt vmcnt(0)" ::: "memory");
;         __syncthreads();
.Ldma_skip_1:
	s_waitcnt lgkmcnt(0)
	ds_read_b64_tr_b16 v[82:83], v230 offset:32768
	ds_read_b64_tr_b16 v[84:85], v229 offset:32768
	ds_read_b64_tr_b16 v[86:87], v228 offset:32768
	ds_read_b64_tr_b16 v[88:89], v227 offset:32768
	ds_read_b64_tr_b16 v[118:119], v234 offset:32768
	ds_read_b64_tr_b16 v[120:121], v233 offset:32768
	ds_read_b64_tr_b16 v[122:123], v232 offset:32768
	ds_read_b64_tr_b16 v[124:125], v231 offset:32768
	v_add_f32_e64 v130, v146, v126
	v_add_f32_e64 v131, v147, v127
	v_mfma_f32_32x32x16_bf16 v[50:65], v[78:81], v[114:117], v[50:65]
	v_exp_f32_e32 v78, v90
	v_exp_f32_e32 v79, v91
	v_exp_f32_e32 v80, v92
	v_exp_f32_e32 v81, v93
	v_exp_f32_e32 v90, v94
	v_exp_f32_e32 v91, v95
	v_exp_f32_e32 v92, v96
	v_exp_f32_e32 v93, v97
	v_pk_add_f32 v[94:95], v[78:79], v[80:81]
	v_cvt_pk_bf16_f32 v78, v78, v79
	v_cvt_pk_bf16_f32 v79, v80, v81
	v_pk_add_f32 v[96:97], v[90:91], v[92:93]
	v_cvt_pk_bf16_f32 v80, v90, v91
	v_cvt_pk_bf16_f32 v81, v92, v93
	s_nop 0
	v_pk_add_f32 v[132:133], v[94:95], v[96:97]
	v_mfma_f32_32x32x16_bf16 v[34:49], v[134:137], v[114:117], v[34:49]
	v_mfma_f32_32x32x16_bf16 v[18:33], v[138:141], v[114:117], v[18:33]
	v_mfma_f32_32x32x16_bf16 v[2:17], v[142:145], v[114:117], v[2:17]
	s_waitcnt lgkmcnt(0)
	ds_read_b64_tr_b16 v[90:91], v230 offset:36864
	ds_read_b64_tr_b16 v[92:93], v229 offset:36864
	ds_read_b64_tr_b16 v[94:95], v228 offset:36864
	ds_read_b64_tr_b16 v[96:97], v227 offset:36864
	ds_read_b64_tr_b16 v[114:115], v234 offset:36864
	ds_read_b64_tr_b16 v[116:117], v233 offset:36864
	ds_read_b64_tr_b16 v[126:127], v232 offset:36864
	ds_read_b64_tr_b16 v[128:129], v231 offset:36864
	v_add_f32_e64 v154, v132, v130
	v_add_f32_e64 v155, v133, v131
	v_mfma_f32_32x32x16_bf16 v[50:65], v[82:85], v[66:69], v[50:65]
	v_mfma_f32_32x32x16_bf16 v[34:49], v[86:89], v[66:69], v[34:49]
	v_mfma_f32_32x32x16_bf16 v[18:33], v[118:121], v[66:69], v[18:33]
	v_mfma_f32_32x32x16_bf16 v[2:17], v[122:125], v[66:69], v[2:17]
	s_waitcnt lgkmcnt(0)
	ds_read_b64_tr_b16 v[66:67], v230 offset:40960
	ds_read_b64_tr_b16 v[68:69], v229 offset:40960
	ds_read_b64_tr_b16 v[82:83], v228 offset:40960
	ds_read_b64_tr_b16 v[84:85], v227 offset:40960
	ds_read_b64_tr_b16 v[86:87], v234 offset:40960
	ds_read_b64_tr_b16 v[88:89], v233 offset:40960
	ds_read_b64_tr_b16 v[118:119], v232 offset:40960
	ds_read_b64_tr_b16 v[120:121], v231 offset:40960
	s_nop 0
	v_mfma_f32_32x32x16_bf16 v[50:65], v[90:93], v[70:73], v[50:65]
	v_mfma_f32_32x32x16_bf16 v[34:49], v[94:97], v[70:73], v[34:49]
	v_mfma_f32_32x32x16_bf16 v[18:33], v[114:117], v[70:73], v[18:33]
	v_mfma_f32_32x32x16_bf16 v[2:17], v[126:129], v[70:73], v[2:17]
	s_waitcnt lgkmcnt(0)
	ds_read_b64_tr_b16 v[70:71], v230 offset:45056
	ds_read_b64_tr_b16 v[72:73], v229 offset:45056
	ds_read_b64_tr_b16 v[90:91], v228 offset:45056
	ds_read_b64_tr_b16 v[92:93], v227 offset:45056
	ds_read_b64_tr_b16 v[94:95], v234 offset:45056
	ds_read_b64_tr_b16 v[96:97], v233 offset:45056
	ds_read_b64_tr_b16 v[114:115], v232 offset:45056
	ds_read_b64_tr_b16 v[116:117], v231 offset:45056
	s_nop 0
	v_mfma_f32_32x32x16_bf16 v[50:65], v[66:69], v[74:77], v[50:65]
	v_mfma_f32_32x32x16_bf16 v[34:49], v[82:85], v[74:77], v[34:49]
	v_mfma_f32_32x32x16_bf16 v[18:33], v[86:89], v[74:77], v[18:33]
	v_mfma_f32_32x32x16_bf16 v[2:17], v[118:121], v[74:77], v[2:17]
	s_waitcnt lgkmcnt(0)
	s_nop 0
	v_mfma_f32_32x32x16_bf16 v[50:65], v[70:73], v[78:81], v[50:65]
	v_mfma_f32_32x32x16_bf16 v[34:49], v[90:93], v[78:81], v[34:49]
	v_mfma_f32_32x32x16_bf16 v[18:33], v[94:97], v[78:81], v[18:33]
	v_mfma_f32_32x32x16_bf16 v[2:17], v[114:117], v[78:81], v[2:17]
	s_addk_i32 s33, 0x80
	v_add_u32_e32 v211, 0x8000, v211
	v_add_u32_e32 v226, 0x8000, v226
	s_add_i32 s57, s57, 1
	s_and_b64 vcc, exec, s[0:1]
	s_waitcnt vmcnt(0)
	s_barrier
	s_cbranch_vccnz .LBB0_677

; __device__ __forceinline__ void attn_unit(const bf16* Hb, const bf16* KD, const bf16* VD, bf16* MIX, int row0, int S, int head, int qb, float lam, const float* dng, float kn0, float kn1, LAS unsigned char* lds, int wave_u) {
;     ...
;         if (t + 2 <= thi) { ATT_DMA(t + 2, 2 * (pbuf ^ 1)); ATT_DMA(t + 3, 2 * (pbuf ^ 1) + 1); }
.LBB0_673:
	v_add_u32_e32 v134, 0x7f, v135
	s_waitcnt lgkmcnt(0)
	v_cvt_f32_i32_e32 v172, v134
	ds_read_b64_tr_b16 v[134:135], v230 offset:4096
	ds_read_b64_tr_b16 v[136:137], v229 offset:4096
	ds_read_b64_tr_b16 v[138:139], v228 offset:4096
	ds_read_b64_tr_b16 v[140:141], v227 offset:4096
	ds_read_b64_tr_b16 v[142:143], v234 offset:4096
	ds_read_b64_tr_b16 v[144:145], v233 offset:4096
	ds_read_b64_tr_b16 v[146:147], v232 offset:4096
	ds_read_b64_tr_b16 v[148:149], v231 offset:4096
	ds_read_b128 v[194:197], v173 offset:32768
	ds_read_b128 v[238:241], v235 offset:32768
	ds_read_b128 v[242:245], v236 offset:32768
	ds_read_b128 v[246:249], v237 offset:32768
	v_mfma_f32_32x32x16_bf16 v[50:65], v[130:133], v[150:153], v[50:65]
	v_exp_f32_e32 v132, v86
	v_exp_f32_e32 v133, v87
	v_exp_f32_e32 v130, v90
	v_exp_f32_e32 v131, v91
	v_mfma_f32_32x32x16_bf16 v[34:49], v[126:129], v[150:153], v[34:49]
	v_exp_f32_e32 v126, v82
	v_exp_f32_e32 v127, v83
	v_exp_f32_e32 v128, v84
	v_exp_f32_e32 v129, v85
	v_mfma_f32_32x32x16_bf16 v[18:33], v[122:125], v[150:153], v[18:33]
	v_cvt_pk_bf16_f32 v122, v126, v127
	v_cvt_pk_bf16_f32 v123, v128, v129
	v_cvt_pk_bf16_f32 v124, v132, v133
	v_mfma_f32_32x32x16_bf16 v[2:17], v[114:117], v[150:153], v[2:17]
	v_exp_f32_e32 v152, v88
	v_exp_f32_e32 v153, v89
	v_exp_f32_e32 v150, v92
	v_exp_f32_e32 v151, v93
	v_cvt_pk_bf16_f32 v125, v152, v153
	v_cvt_pk_bf16_f32 v114, v130, v131
	v_cvt_pk_bf16_f32 v115, v150, v151
	s_waitcnt lgkmcnt(0)
	v_mfma_f32_32x32x16_bf16 v[66:81], v[194:197], v[98:101], v[66:81]
	v_exp_f32_e32 v194, v94
	v_exp_f32_e32 v195, v95
	v_exp_f32_e32 v196, v96
	v_exp_f32_e32 v197, v97
	v_cvt_pk_bf16_f32 v116, v194, v195
	v_cvt_pk_bf16_f32 v117, v196, v197
	v_mfma_f32_32x32x16_bf16 v[66:81], v[238:241], v[102:105], v[66:81]
	v_mfma_f32_32x32x16_bf16 v[66:81], v[242:245], v[106:109], v[66:81]
	v_mfma_f32_32x32x16_bf16 v[66:81], v[246:249], v[110:113], v[66:81]
	s_cmp_le_i32 s73, s74
	s_cbranch_scc0 .Ldma_skip_0
	s_xor_b32 s84, s59, 0x10000
	s_add_i32 s84, s76, s84
	v_readlane_b32 s80, v251, 44
	v_readlane_b32 s81, v251, 45
	v_readlane_b32 s82, v251, 46
	v_readlane_b32 s83, v251, 47
	v_add_u32_e32 v250, s75, v226
	v_add_u32_e32 v254, s75, v211
	v_add_u32_e32 v250, 0x8000, v250
	v_add_u32_e32 v254, 0x8000, v254
	s_nop 4
	s_add_i32 m0, s84, 0x0
	s_nop 0
	global_load_lds_dwordx4 v250, s[80:81]
	s_add_i32 m0, s84, 0x400
	s_nop 0
	global_load_lds_dwordx4 v254, s[80:81]
	s_add_i32 m0, s84, 0x4000
	s_nop 0
	global_load_lds_dwordx4 v250, s[82:83]
	s_add_i32 m0, s84, 0x4400
	s_nop 0
	global_load_lds_dwordx4 v254, s[82:83]
.Ldma_skip_0:
	s_andn2_b64 vcc, exec, s[2:3]
	s_mov_b64 s[2:3], -1
	s_cbranch_vccnz .LBB0_675
	v_add_f32_e32 v96, 1.0, v172
	v_pk_add_f32 v[82:83], v[172:173], s[6:7] op_sel_hi:[0,1]
	v_pk_add_f32 v[84:85], v[172:173], s[8:9] op_sel_hi:[0,1]
	v_pk_add_f32 v[86:87], v[172:173], s[10:11] op_sel_hi:[0,1]
	v_pk_add_f32 v[88:89], v[172:173], s[12:13] op_sel_hi:[0,1]
	v_pk_add_f32 v[90:91], v[172:173], s[14:15] op_sel_hi:[0,1]
	v_pk_add_f32 v[92:93], v[172:173], s[16:17] op_sel_hi:[0,1]
	v_pk_add_f32 v[94:95], v[172:173], s[18:19] op_sel_hi:[0,1]
	v_and_b32_e32 v83, 0x7fffffff, v83
	v_and_b32_e32 v82, 0x7fffffff, v82
	v_and_b32_e32 v85, 0x7fffffff, v85
	v_and_b32_e32 v84, 0x7fffffff, v84
	v_and_b32_e32 v87, 0x7fffffff, v87
	v_and_b32_e32 v86, 0x7fffffff, v86
	v_and_b32_e32 v89, 0x7fffffff, v89
	v_and_b32_e32 v88, 0x7fffffff, v88
	v_and_b32_e32 v91, 0x7fffffff, v91
	v_and_b32_e32 v90, 0x7fffffff, v90
	v_and_b32_e32 v93, 0x7fffffff, v93
	v_and_b32_e32 v92, 0x7fffffff, v92
	v_and_b32_e32 v95, 0x7fffffff, v95
	v_and_b32_e32 v94, 0x7fffffff, v94
	v_and_b32_e32 v238, 0x7fffffff, v172
	v_and_b32_e32 v239, 0x7fffffff, v96
	v_mov_b32_e32 v175, v174
	v_pk_fma_f32 v[96:97], v[94:95], v[174:175], v[192:193]
	v_pk_fma_f32 v[94:95], v[92:93], v[174:175], v[190:191]
	v_pk_fma_f32 v[92:93], v[90:91], v[174:175], v[188:189]
	v_pk_fma_f32 v[90:91], v[88:89], v[174:175], v[186:187]
	v_pk_fma_f32 v[88:89], v[86:87], v[174:175], v[184:185]
	v_pk_fma_f32 v[86:87], v[84:85], v[174:175], v[182:183]
	v_pk_fma_f32 v[84:85], v[82:83], v[174:175], v[180:181]
	v_pk_fma_f32 v[82:83], v[238:239], v[178:179], v[176:177]
	s_mov_b64 s[2:3], 0
